# v55 plus unit-header: has_next as a scalar compare (no 64-bit VALU compares / wait states) and unsigned shift/mask forms of the XCD remap
# baseline (speedup 1.0000x reference)
;     __device__ __forceinline__ size_t aoff(const Unit& u) const { return (size_t)u.pm * bm * lda * 2; }
;     __device__ __forceinline__ size_t boff(const Unit& u) const { return (size_t)u.pn * BM * ldb * 2; }
;     __device__ __forceinline__ size_t aoff(const Unit& u) const { return ((size_t)u.pm * BM * lda + (size_t)u.pn * akoff) * 2; }
;     __device__ __forceinline__ size_t boff(const Unit& u) const { return (size_t)u.pn * BM * ldb * 2; }
;     __device__ __forceinline__ size_t aoff(const Unit& u) const { return ((size_t)u.pm * BM * lda + (size_t)(u.pn >> 1) * akoff) * 2; }
;     __device__ __forceinline__ size_t boff(const Unit& u) const { return (size_t)u.pn * BM * ldb * 2; }
;     __device__ bool next(int i, Unit& u) const {
;         const long L = (long)i * G + c; if (L >= nwg) return false;
;         int wgid = (int)L; { const int q = nwg / NXCD, r = nwg % NXCD, xcd = wgid % NXCD, off = wgid / NXCD; wgid = (xcd < r ? xcd * (q + 1) : r * (q + 1) + (xcd - r) * q) + off; }
;         const int nig = WGM * nN, gid = wgid / nig, fm = gid * WGM, gsz = (nM - fm) < WGM ? (nM - fm) : WGM;
;         u.pm = fm + ((wgid % nig) % gsz); u.pn = (wgid % nig) / gsz; return true;
;     }
;     ...
;         const bool has_next = S.next(ui + 1, nxt);
;         const char* nA = has_next ? (const char*)g.A + S.aoff(nxt) : cA; const char* nB = has_next ? (const char*)g.Bt + S.boff(nxt) : cB;
.LBB0_195:
	s_add_i32 s70, s70, 1
	s_mul_i32 s2, s70, s62
	s_mul_hi_u32 s3, s70, s53
	s_add_i32 s3, s3, s2
	s_mul_i32 s2, s70, s53
	v_readlane_b32 s4, v255, 29
	s_add_u32 s2, s2, s4
	s_addc_u32 s3, s3, s63
	s_cmp_lt_u32 s2, 0x900
	s_cselect_b64 s[4:5], -1, 0
	s_cselect_b32 s101, -1, 0
	s_cbranch_scc0 .LBB0_197
	s_lshr_b32 s9, s2, 3
	s_and_b32 s2, s2, 7
	s_mul_i32 s2, s2, 0x120
	s_add_i32 s2, s2, s9
	s_ashr_i32 s3, s2, 31
	s_lshr_b32 s3, s3, 24
	s_add_i32 s3, s2, s3
	s_ashr_i32 s9, s3, 8
	s_lshl_b32 s9, s9, 3
	s_sub_i32 s20, 0x48, s9
	s_min_i32 s21, s20, 8
	s_and_b32 s3, s3, 0xffffff00
	s_sub_i32 s2, s2, s3
	s_ashr_i32 s20, s2, 3
	s_and_b32 s2, s2, 7
	s_add_i32 s22, s9, s2

;     __device__ bool next(int i, Unit& u) const {
;         const long L = (long)i * G + c; if (L >= nwg) return false;
;         int wgid = (int)L; { const int q = nwg / NXCD, r = nwg % NXCD, xcd = wgid % NXCD, off = wgid / NXCD; wgid = (xcd < r ? xcd * (q + 1) : r * (q + 1) + (xcd - r) * q) + off; }
;         const int nig = WGM * nN, gid = wgid / nig, fm = gid * WGM, gsz = (nM - fm) < WGM ? (nM - fm) : WGM;
;         u.pm = fm + ((wgid % nig) % gsz); u.pn = (wgid % nig) / gsz; return true;
;     }
.LBB0_698:
	s_add_i32 s23, s23, 1
	s_mul_i32 s2, s23, s75
	s_mul_hi_u32 s3, s23, s53
	s_add_i32 s3, s3, s2
	s_mul_i32 s2, s23, s53
	v_readlane_b32 s4, v255, 29
	s_add_u32 s2, s2, s4
	s_addc_u32 s3, s3, s78
	s_cmp_lt_u32 s2, 0x288
	s_cselect_b64 s[4:5], -1, 0
	s_cselect_b32 s101, -1, 0
	s_cbranch_scc0 .LBB0_700
	s_lshr_b32 s9, s2, 3
	s_and_b32 s2, s2, 7
	s_mul_i32 s2, s2, 0x51
	s_add_i32 s2, s2, s9
	s_mul_hi_i32 s3, s2, 0x38e38e39
	s_lshr_b32 s9, s3, 31
	s_ashr_i32 s3, s3, 4
	s_add_i32 s3, s3, s9
	s_lshl_b32 s9, s3, 3
	s_sub_i32 s26, 0x48, s9
	s_min_i32 s27, s26, 8
	s_mulk_i32 s3, 0x48
	s_sub_i32 s2, s2, s3
	s_ashr_i32 s26, s2, 3
	s_and_b32 s2, s2, 7
	s_add_i32 s28, s9, s2

;     __device__ bool next(int i, Unit& u) const {
;         const long L = (long)i * G + c; if (L >= nwg) return false;
;         int wgid = (int)L; { const int q = nwg / NXCD, r = nwg % NXCD, xcd = wgid % NXCD, off = wgid / NXCD; wgid = (xcd < r ? xcd * (q + 1) : r * (q + 1) + (xcd - r) * q) + off; }
;         const int nig = WGM * nN, gid = wgid / nig, fm = gid * WGM, gsz = (nM - fm) < WGM ? (nM - fm) : WGM;
;         u.pm = fm + ((wgid % nig) % gsz); u.pn = (wgid % nig) / gsz; return true;
;     }
.LBB0_1189:
	s_add_i32 s47, s47, 1
	s_mul_i32 s2, s47, s92
	s_mul_hi_u32 s3, s47, s53
	s_add_i32 s3, s3, s2
	s_mul_i32 s2, s47, s53
	v_readlane_b32 s4, v255, 29
	s_add_u32 s2, s2, s4
	s_addc_u32 s3, s3, s93
	s_cmp_lt_u32 s2, 0x1b0
	s_cselect_b64 s[4:5], -1, 0
	s_cselect_b32 s101, -1, 0
	s_cbranch_scc0 .LBB0_1191
	s_lshr_b32 s7, s2, 3
	s_and_b32 s2, s2, 7
	s_mul_i32 s2, s2, 54
	s_add_i32 s2, s2, s7
	s_mul_hi_i32 s3, s2, 0x2aaaaaab
	s_lshr_b32 s7, s3, 31
	s_ashr_i32 s3, s3, 3
	s_add_i32 s3, s3, s7
	s_lshl_b32 s7, s3, 3
	s_sub_i32 s9, 0x48, s7
	s_min_i32 s9, s9, 8
	s_mul_i32 s3, s3, 48
	s_sub_i32 s2, s2, s3
	s_ashr_i32 s24, s2, 3
	s_and_b32 s2, s2, 7
	s_add_i32 s26, s7, s2

;     __device__ bool next(int i, Unit& u) const {
;         const long L = (long)i * G + c; if (L >= nwg) return false;
;         int wgid = (int)L; { const int q = nwg / NXCD, r = nwg % NXCD, xcd = wgid % NXCD, off = wgid / NXCD; wgid = (xcd < r ? xcd * (q + 1) : r * (q + 1) + (xcd - r) * q) + off; }
;         const int nig = WGM * nN, gid = wgid / nig, fm = gid * WGM, gsz = (nM - fm) < WGM ? (nM - fm) : WGM;
;         u.pm = fm + ((wgid % nig) % gsz); u.pn = (wgid % nig) / gsz; return true;
;     }
.LBB0_1445:
	s_add_i32 s69, s69, 1
	s_mul_i32 s2, s69, s68
	s_mul_hi_u32 s3, s69, s53
	s_add_i32 s3, s3, s2
	s_mul_i32 s2, s69, s53
	v_readlane_b32 s4, v255, 29
	s_add_u32 s2, s2, s4
	s_addc_u32 s3, s3, s26
	s_cmp_lt_u32 s2, 0x200
	s_cselect_b64 s[6:7], -1, 0
	s_cselect_b32 s101, -1, 0
	s_cbranch_scc0 .LBB0_1451
	s_ashr_i32 s3, s2, 31
	s_lshr_b32 s3, s3, 29
	s_add_i32 s4, s2, s3
	s_and_b32 s3, s4, -8
	s_sub_i32 s5, s2, s3
	s_cmp_gt_i32 s5, -1
	s_mov_b64 s[2:3], -1
	s_cbranch_scc0 .LBB0_1448
	s_lshl_b32 s14, s5, 6
	s_mov_b64 s[2:3], 0

;     __device__ bool next(int i, Unit& u) const {
;         const long L = (long)i * G + c; if (L >= nwg) return false;
;         int wgid = (int)L; { const int q = nwg / NXCD, r = nwg % NXCD, xcd = wgid % NXCD, off = wgid / NXCD; wgid = (xcd < r ? xcd * (q + 1) : r * (q + 1) + (xcd - r) * q) + off; }
;         const int nig = WGM * nN, gid = wgid / nig, fm = gid * WGM, gsz = (nM - fm) < WGM ? (nM - fm) : WGM;
;         u.pm = fm + ((wgid % nig) % gsz); u.pn = (wgid % nig) / gsz; return true;
;     }
.LBB0_1645:
	s_add_i32 s54, s54, 1
	s_mul_i32 s2, s54, s48
	s_mul_hi_u32 s3, s54, s53
	s_add_i32 s3, s3, s2
	s_mul_i32 s2, s54, s53
	v_readlane_b32 s6, v255, 29
	s_add_u32 s2, s2, s6
	s_addc_u32 s3, s3, s49
	s_cmp_lt_u32 s2, 0x300
	s_cselect_b64 s[8:9], -1, 0
	s_cselect_b32 s101, -1, 0
	s_cbranch_scc0 .LBB0_1647
	s_lshr_b32 s6, s2, 3
	s_and_b32 s2, s2, 7
	s_mul_i32 s2, s2, 0x60
	s_add_i32 s2, s2, s6
	s_ashr_i32 s3, s2, 31
	s_lshr_b32 s3, s3, 26
	s_add_i32 s3, s2, s3
	s_ashr_i32 s6, s3, 6
	s_lshl_b32 s6, s6, 3
	s_sub_i32 s7, 0x60, s6
	s_min_i32 s7, s7, 8
	s_andn2_b32 s3, s3, 63
	s_sub_i32 s2, s2, s3
	s_ashr_i32 s14, s2, 3
	s_and_b32 s2, s2, 7
	s_add_i32 s56, s6, s2

;     __device__ bool next(int i, Unit& u) const {
;         const long L = (long)i * G + c; if (L >= nwg) return false;
;         int wgid = (int)L; { const int q = nwg / NXCD, r = nwg % NXCD, xcd = wgid % NXCD, off = wgid / NXCD; wgid = (xcd < r ? xcd * (q + 1) : r * (q + 1) + (xcd - r) * q) + off; }
;         const int nig = WGM * nN, gid = wgid / nig, fm = gid * WGM, gsz = (nM - fm) < WGM ? (nM - fm) : WGM;
;         u.pm = fm + ((wgid % nig) % gsz); u.pn = (wgid % nig) / gsz; return true;
;     }
.LBB0_1770:
	s_add_i32 s78, s78, 1
	s_mul_i32 s2, s78, s89
	s_mul_hi_u32 s3, s78, s53
	s_add_i32 s3, s3, s2
	s_mul_i32 s2, s78, s53
	s_add_u32 s2, s2, s46
	s_addc_u32 s3, s3, s52
	s_cmp_lt_u32 s2, 0xc60
	s_cselect_b64 s[6:7], -1, 0
	s_cselect_b32 s101, -1, 0
	s_cbranch_scc0 .LBB0_1772
	s_lshr_b32 s9, s2, 3
	s_and_b32 s2, s2, 7
	s_mul_i32 s2, s2, 0x18c
	s_add_i32 s2, s2, s9
	s_mul_hi_i32 s3, s2, 0x2e8ba2e9
	s_lshr_b32 s9, s3, 31
	s_ashr_i32 s3, s3, 6
	s_add_i32 s3, s3, s9
	s_lshl_b32 s9, s3, 3
	s_sub_i32 s11, 0x48, s9
	s_min_i32 s11, s11, 8
	s_mulk_i32 s3, 0x160
	s_sub_i32 s2, s2, s3
	s_ashr_i32 s36, s2, 3
	s_and_b32 s2, s2, 7
	s_add_i32 s40, s9, s2

;     __device__ bool next(int i, Unit& u) const {
;         const long L = (long)i * G + c; if (L >= nwg) return false;
;         int wgid = (int)L; { const int q = nwg / NXCD, r = nwg % NXCD, xcd = wgid % NXCD, off = wgid / NXCD; wgid = (xcd < r ? xcd * (q + 1) : r * (q + 1) + (xcd - r) * q) + off; }
;         const int nig = WGM * nN, gid = wgid / nig, fm = gid * WGM, gsz = (nM - fm) < WGM ? (nM - fm) : WGM;
;         u.pm = fm + ((wgid % nig) % gsz); u.pn = (wgid % nig) / gsz; return true;
;     }
.LBB0_2151:
	s_add_i32 s54, s54, 1
	s_mul_i32 s2, s54, s48
	s_mul_hi_u32 s3, s54, s53
	s_add_i32 s3, s3, s2
	s_mul_i32 s2, s54, s53
	v_readlane_b32 s4, v255, 29
	s_add_u32 s2, s2, s4
	s_addc_u32 s3, s3, s49
	s_cmp_lt_u32 s2, 0x300
	s_cselect_b64 s[6:7], -1, 0
	s_cselect_b32 s101, -1, 0
	s_cbranch_scc0 .LBB0_2153
	s_lshr_b32 s4, s2, 3
	s_and_b32 s2, s2, 7
	s_mul_i32 s2, s2, 0x60
	s_add_i32 s2, s2, s4
	s_ashr_i32 s3, s2, 31
	s_lshr_b32 s3, s3, 26
	s_add_i32 s3, s2, s3
	s_ashr_i32 s4, s3, 6
	s_lshl_b32 s4, s4, 3
	s_sub_i32 s5, 0x60, s4
	s_min_i32 s5, s5, 8
	s_andn2_b32 s3, s3, 63
	s_sub_i32 s2, s2, s3
	s_ashr_i32 s56, s2, 3
	s_and_b32 s2, s2, 7
	s_add_i32 s57, s4, s2
